# P0: rope table computed by workgroups 192..255 (one weight strip fewer) instead of 0..63
# speedup vs baseline: 1.0095x; 1.0022x over previous
; __device__ __forceinline__ void p0_prep(const Params& p, LAS unsigned char* lds) {
;     ...
;     float* RC = (float*)(ws + WS_ROPE); float* RS = RC + 2048 * 16;
;     for (int idx = bid * 512 + tid; idx < 2048 * 16; idx += G * 512) {
;         const int pos = idx >> 4, i = idx & 15;
;         const float inv = powf(500000.0f, -(float)(2 * i) / 32.0f);
;         const float ang = (float)pos * inv;
;         RC[idx] = cosf(ang); RS[idx] = sinf(ang);
;     }
.LBB0_48:
	s_or_b64 exec, exec, s[14:15]
	s_mov_b32 s98, s84
	s_cmpk_lg_i32 s82, 0x100
	s_cbranch_scc1 .Lrope_nomap
	s_add_i32 s98, s84, 64
	s_and_b32 s98, s98, 0xff
.Lrope_nomap:
	v_lshl_add_u32 v0, s98, 9, v212
	s_mov_b32 s0, 0x8000
	v_cmp_gt_i32_e32 vcc, s0, v0
	s_and_saveexec_b64 s[8:9], vcc
	s_cbranch_execz .LBB0_59
	s_lshl_b32 s12, s82, 9
	v_ashrrev_i32_e32 v1, 31, v0
	v_lshl_add_u64 v[2:3], v[0:1], 2, s[88:89]
	s_mov_b64 s[0:1], 0xff80000
	s_ashr_i32 s13, s12, 31
	v_lshlrev_b32_e32 v1, 1, v212
	v_lshl_add_u64 v[2:3], v[2:3], 0, s[0:1]
	s_lshl_b64 s[14:15], s[12:13], 2
	v_lshl_add_u32 v1, s98, 10, v1
	s_lshl_b32 s13, s82, 10
	s_mov_b64 s[16:17], 0
	v_mov_b32_e32 v6, 0x48f42400
	s_mov_b32 s20, 0x3f2aaaab
	v_mov_b32_e32 v7, 0x3e91f4c4
	s_mov_b32 s21, 0x3f317218
	s_movk_i32 s22, 0x204
	s_mov_b32 s23, 0x7f800000
	s_mov_b32 s24, 0x42b17218
	v_mov_b32_e32 v8, 0x37000000
	s_mov_b32 s25, 0x3fb8aa3b
	s_mov_b32 s26, 0xc2ce8ed0
	v_mov_b32_e32 v9, 0x7f800000
	s_brev_b32 s27, 18
	s_mov_b32 s28, 0xfe5163ab
	v_mov_b32_e32 v5, 0
	s_mov_b32 s29, 0x3c439041
	s_mov_b32 s30, 0xdb629599
	s_mov_b32 s31, 0xf534ddc0
	s_mov_b32 s33, 0xfc2757d1
	s_mov_b32 s34, 0x4e441529
	s_mov_b32 s35, 0xa2f9836e
	s_mov_b32 s36, 0x3fc90fda
	s_mov_b32 s37, 0x3f22f983
	s_mov_b32 s38, 0xbfc90fda
	v_mov_b32_e32 v10, 0x3c0881c4
	v_mov_b32_e32 v11, 0xbab64f3b
	s_brev_b32 s39, 1
	s_movk_i32 s40, 0x1f8
	s_movk_i32 s41, 0x7fff
	v_not_b32_e32 v12, 63
	v_not_b32_e32 v13, 31
	v_mov_b32_e32 v14, 0x7fc00000
	s_branch .LBB0_51
